# T15 double pipeline in MLA loop: QK of tile i overlapped with softmax+PV of tile i-1, V through 3 LDS buffers, fixed softmax shift dropped (cancels in O/l)
# speedup vs baseline: 1.0027x; 1.0026x over previous
; #define MFMA32(a, b, c) __builtin_amdgcn_mfma_f32_32x32x16_bf16((a), (b), (c), 0, 0, 0)
; #define AT_LOAD(SET, IT) { const int kl_ = AT_KB(IT); \
;     _Pragma("unroll") for (int i = 0; i < KPT; ++i) kreg[SET][i] = *(const u32x4*)(Kg + (size_t)kl_ * DQK + (tid + 256 * i) * 8); \
;     _Pragma("unroll") for (int i = 0; i < 2; ++i) vreg[SET][i] = *(const u32x4*)(Vg + (size_t)kl_ * 64 + (tid + 256 * i) * 8); \
;     __builtin_amdgcn_sched_barrier(0); }
; template <int DQK, bool SB, bool SMAX>
; DI void attn_item(const Params& p, char* smem, int bh, int qb, float Mb) {
;     ...
;   f32x16 O[2];
; #pragma unroll
;   for (int db = 0; db < 2; ++db)
; #pragma unroll
;     for (int i = 0; i < 16; ++i) O[db][i] = 0.f;
;   float m = -__builtin_huge_valf(), lsum = 0.f, carry = 0.f;
;   f32x16 negM;
; #pragma unroll
;   for (int i = 0; i < 16; ++i) negM[i] = -Mb;
;   u32x4 kreg[1][KPT], vreg[1][2];
;     ...
;   const int blk = (lane >> 4) & 1, tq = (lane & 15) >> 2, tp = lane & 3;
;   const int voff = (4 * h + tq) * VSTR + 16 * blk + 4 * tp;
;   AT_LOAD(0, 0)
;   AT_WRITE(0, 0)
;   AT_LOAD(0, 1)
;   __syncthreads();
;   bool stop = false;
;   for (int it2 = 0; it2 < nt && !stop; it2 += 2) {
; #pragma unroll
;    for (int st2 = 0; st2 < 2; ++st2) {
;     const int it = it2 + st2;
;     const int kb0 = AT_KB(it);
;     const bf16_t* kc = Ks + st2 * KBUF;
;     const bf16_t* vc = Vs + st2 * VBUF;
;     const bool active = kb0 < qw0 + 32;
;     f32x16 st[2];
;     if (active) {
; #pragma unroll
;       for (int kb = 0; kb < 2; ++kb)
; #pragma unroll
;         for (int i = 0; i < 16; ++i) st[kb][i] = SMAX ? negM[i] : 0.f;
; #pragma unroll
;       for (int ks = 0; ks < NKS; ++ks)
; #pragma unroll
;         for (int kb = 0; kb < 2; ++kb) {
;           const bf16x8 a = *(const bf16x8*)(kc + (kb * 32 + r) * KSTR + ks * 16 + h * 8);
;           st[kb] = MFMA32(a, qf[ks], st[kb]);
;         }
;     }
;     __builtin_amdgcn_sched_barrier(0);
;     AT_WRITE(0, st2 ^ 1)
;     AT_LOAD(0, (it + 2 < nt) ? it + 2 : nt - 1)
.LBB0_470:
	s_and_b64 vcc, exec, s[2:3]
	s_cbranch_vccz .LBB0_425
	global_load_dwordx4 v[132:135], v[186:187], off
	global_load_dwordx4 v[136:139], v[188:189], off
	global_load_dwordx4 v[140:143], v[190:191], off
	global_load_dwordx4 v[144:147], v[192:193], off
	global_load_dwordx4 v[148:151], v[194:195], off
	s_waitcnt vmcnt(9)
	ds_write_b128 v206, v[112:115]
	s_waitcnt vmcnt(8)
	ds_write_b128 v207, v[116:119]
	s_waitcnt vmcnt(7)
	ds_write_b128 v208, v[120:123]
	s_waitcnt vmcnt(6)
	ds_write_b128 v203, v[124:127] offset:26624
	s_waitcnt vmcnt(5)
	ds_write_b128 v204, v[128:131] offset:26624
	s_and_b64 vcc, exec, s[12:13]
	s_waitcnt lgkmcnt(0)
	s_barrier
	s_cbranch_vccnz .LBB0_423
	v_mov_b32_e32 v16, v177
	v_mov_b32_e32 v17, v177
	v_mov_b32_e32 v18, v177
	v_mov_b32_e32 v19, v177
	v_mov_b32_e32 v20, v177
	v_mov_b32_e32 v21, v177
	v_mov_b32_e32 v22, v177
	v_mov_b32_e32 v23, v177
	v_mov_b32_e32 v24, v177
	v_mov_b32_e32 v25, v177
	v_mov_b32_e32 v26, v177
	v_mov_b32_e32 v27, v177
	v_mov_b32_e32 v28, v177
	v_mov_b32_e32 v29, v177
	v_mov_b32_e32 v30, v177
	v_mov_b32_e32 v31, v177
	v_mov_b32_e32 v32, v177
	v_mov_b32_e32 v33, v177
	v_mov_b32_e32 v34, v177
	v_mov_b32_e32 v35, v177
	v_mov_b32_e32 v36, v177
	v_mov_b32_e32 v37, v177
	v_mov_b32_e32 v38, v177
	v_mov_b32_e32 v39, v177
	v_mov_b32_e32 v40, v177
	v_mov_b32_e32 v41, v177
	v_mov_b32_e32 v42, v177
	v_mov_b32_e32 v43, v177
	v_mov_b32_e32 v44, v177
	v_mov_b32_e32 v45, v177
	v_mov_b32_e32 v46, v177
	v_mov_b32_e32 v47, v177
	v_mov_b32_e32 v152, 0
	v_add_u32_e32 v153, v178, v202
	v_add_u32_e32 v154, v198, v200
	v_readfirstlane_b32 s20, v211
	s_add_i32 s4, s1, -1
	s_lshr_b32 s21, s16, 1
	s_mov_b32 s14, 2
	s_mov_b32 s26, 0xb000
	s_mov_b32 s27, 0x6800
	s_mov_b32 s28, 0x8c00
	v_add_u32_e32 v155, s26, v154
	v_add_u32_e32 v215, s28, v203
	v_add_u32_e32 v233, s28, v204
	ds_read_b128 v[216:219], v153
	ds_read_b128 v[220:223], v153 offset:6656
	ds_read_b128 v[228:231], v153 offset:32
	s_min_i32 s2, s14, s4
	s_lshl_b32 s2, s2, 6
	s_ashr_i32 s3, s2, 31
	v_mad_i64_i32 v[116:117], s[18:19], s2, v209, v[182:183]
	v_add_co_u32_e32 v120, vcc, s6, v116
	s_lshl_b64 s[2:3], s[2:3], 7
	s_nop 0
	v_addc_co_u32_e32 v121, vcc, 0, v117, vcc
	v_lshl_add_u64 v[124:125], v[184:185], 0, s[2:3]
	v_add_co_u32_e32 v128, vcc, 0x1000, v124
	global_load_dwordx4 v[112:115], v[116:117], off
	s_nop 0
	v_addc_co_u32_e32 v129, vcc, 0, v125, vcc
	global_load_dwordx4 v[116:119], v[120:121], off offset:-4096
	s_nop 0
	global_load_dwordx4 v[120:123], v[120:121], off
	s_nop 0
	global_load_dwordx4 v[124:127], v[124:125], off
	s_nop 0
	global_load_dwordx4 v[128:131], v[128:129], off
	s_waitcnt vmcnt(9)
	ds_write_b128 v206, v[132:135] offset:13312
	s_waitcnt vmcnt(8)
	ds_write_b128 v207, v[136:139] offset:13312
	s_waitcnt vmcnt(7)
	ds_write_b128 v208, v[140:143] offset:13312
	s_waitcnt vmcnt(6)
	ds_write_b128 v215, v[144:147]
	s_waitcnt vmcnt(5)
	ds_write_b128 v233, v[148:151]
	s_waitcnt lgkmcnt(7)
	v_mfma_f32_32x32x16_bf16 v[48:63], v[216:219], v[80:83], 0
	ds_read_b128 v[216:219], v153 offset:6688
	s_waitcnt lgkmcnt(7)
	v_mfma_f32_32x32x16_bf16 v[64:79], v[220:223], v[80:83], 0
	ds_read_b128 v[220:223], v153 offset:64
	s_waitcnt lgkmcnt(7)
	v_mfma_f32_32x32x16_bf16 v[48:63], v[228:231], v[84:87], v[48:63]
	ds_read_b128 v[228:231], v153 offset:6720
	s_waitcnt lgkmcnt(2)
	v_mfma_f32_32x32x16_bf16 v[64:79], v[216:219], v[84:87], v[64:79]
	ds_read_b128 v[216:219], v153 offset:96
	s_waitcnt lgkmcnt(2)
	v_mfma_f32_32x32x16_bf16 v[48:63], v[220:223], v[88:91], v[48:63]
	ds_read_b128 v[220:223], v153 offset:6752
	s_waitcnt lgkmcnt(2)
	v_mfma_f32_32x32x16_bf16 v[64:79], v[228:231], v[88:91], v[64:79]
	ds_read_b128 v[228:231], v153 offset:128
	s_waitcnt lgkmcnt(2)
	v_mfma_f32_32x32x16_bf16 v[48:63], v[216:219], v[92:95], v[48:63]
	ds_read_b128 v[216:219], v153 offset:6784
	s_waitcnt lgkmcnt(2)
	v_mfma_f32_32x32x16_bf16 v[64:79], v[220:223], v[92:95], v[64:79]
	ds_read_b128 v[220:223], v153 offset:160
	s_waitcnt lgkmcnt(2)
	v_mfma_f32_32x32x16_bf16 v[48:63], v[228:231], v[104:107], v[48:63]
	ds_read_b128 v[228:231], v153 offset:6816
	s_waitcnt lgkmcnt(2)
	v_mfma_f32_32x32x16_bf16 v[64:79], v[216:219], v[104:107], v[64:79]
	s_waitcnt lgkmcnt(1)
	v_mfma_f32_32x32x16_bf16 v[48:63], v[220:223], v[108:111], v[48:63]
	s_waitcnt lgkmcnt(0)
	v_mfma_f32_32x32x16_bf16 v[64:79], v[228:231], v[108:111], v[64:79]
	s_waitcnt lgkmcnt(0)
	s_barrier
	s_mov_b32 s29, s26
	s_mov_b32 s26, s27
	s_mov_b32 s27, s28
	s_mov_b32 s28, s29
	s_add_i32 s14, s14, 1
	s_cmp_eq_u32 s21, 0
	s_cbranch_scc1 .Lt15_tail
; #define MFMA32(a, b, c) __builtin_amdgcn_mfma_f32_32x32x16_bf16((a), (b), (c), 0, 0, 0)
; DI unsigned pk_bf16(float lo, float hi) { f32x2 v = {lo, hi}; bf2_t b = __builtin_convertvector(v, bf2_t); return __builtin_bit_cast(unsigned, b); }
; template <int DQK, bool SB, bool SMAX>
; DI void attn_item(const Params& p, char* smem, int bh, int qb, float Mb) {
;     ...
;     if (active) {
; #pragma unroll
;       for (int kb = 0; kb < 2; ++kb)
; #pragma unroll
;         for (int i = 0; i < 16; ++i) st[kb][i] = SMAX ? negM[i] : 0.f;
; #pragma unroll
;       for (int ks = 0; ks < NKS; ++ks)
; #pragma unroll
;         for (int kb = 0; kb < 2; ++kb) {
;           const bf16x8 a = *(const bf16x8*)(kc + (kb * 32 + r) * KSTR + ks * 16 + h * 8);
;           st[kb] = MFMA32(a, qf[ks], st[kb]);
;         }
;     }
;     __builtin_amdgcn_sched_barrier(0);
;     AT_WRITE(0, st2 ^ 1)
;     AT_LOAD(0, (it + 2 < nt) ? it + 2 : nt - 1)
;     if (active) {
;       const bool diag = (kb0 + 64 > qw0);
;       bf16x8 pk[4];
;       if (!SB) {
;         if (diag) {
; #pragma unroll
;           for (int kb = 0; kb < 2; ++kb)
; #pragma unroll
;             for (int i = 0; i < 16; ++i) { const int key = kb0 + kb * 32 + crow(i, h); if (key > query) st[kb][i] = -__builtin_huge_valf(); }
;         }
;         if (SMAX) {
;           float ps = 0.f;
; #pragma unroll
;           for (int kb = 0; kb < 2; ++kb)
; #pragma unroll
;             for (int i = 0; i < 16; ++i) { const float pv = fast_exp2(st[kb][i]); st[kb][i] = pv; ps += pv; }
;           lsum += ps;
;     ...
; #pragma unroll
;       for (int kb = 0; kb < 2; ++kb)
; #pragma unroll
;         for (int s = 0; s < 2; ++s) {
;           u32x4 w;
; #pragma unroll
;           for (int e = 0; e < 4; ++e) w[e] = pk_bf16(st[kb][8 * s + 2 * e], st[kb][8 * s + 2 * e + 1]);
;           pk[kb * 2 + s] = __builtin_bit_cast(bf16x8, w);
;         }
; #pragma unroll
;       for (int kk = 0; kk < 4; ++kk)
; #pragma unroll
;         for (int db = 0; db < 2; ++db) {
;           const s16x4 v0 = __builtin_amdgcn_ds_read_tr16_b64_v4i16((lds_s16x4*)(vc + voff + (16 * kk) * VSTR + 32 * db));
;           const s16x4 v1 = __builtin_amdgcn_ds_read_tr16_b64_v4i16((lds_s16x4*)(vc + voff + (16 * kk + 8) * VSTR + 32 * db));
;           const bf16x8 vf = __builtin_shufflevector(v0, v1, 0, 1, 2, 3, 4, 5, 6, 7);
;           O[db] = MFMA32(vf, pk[kk], O[db]);
;         }
.Lt15_loop:
	v_add_u32_e32 v155, s26, v154
	v_add_u32_e32 v215, s28, v203
	v_add_u32_e32 v233, s28, v204
	ds_read_b128 v[216:219], v153 offset:13312
	ds_read_b128 v[220:223], v153 offset:19968
	ds_read_b128 v[228:231], v153 offset:13344
	ds_read_b64_tr_b16 v[236:237], v155
	ds_read_b64_tr_b16 v[238:239], v155 offset:1152
	ds_read_b64_tr_b16 v[244:245], v155 offset:64
	ds_read_b64_tr_b16 v[246:247], v155 offset:1216
	ds_read_b64_tr_b16 v[248:249], v155 offset:2304
	ds_read_b64_tr_b16 v[250:251], v155 offset:3456
	s_min_i32 s2, s14, s4
	s_lshl_b32 s2, s2, 6
	s_ashr_i32 s3, s2, 31
	v_mad_i64_i32 v[136:137], s[18:19], s2, v209, v[182:183]
	v_add_co_u32_e32 v140, vcc, s6, v136
	s_lshl_b64 s[2:3], s[2:3], 7
	s_nop 0
	v_addc_co_u32_e32 v141, vcc, 0, v137, vcc
	v_lshl_add_u64 v[144:145], v[184:185], 0, s[2:3]
	v_add_co_u32_e32 v148, vcc, 0x1000, v144
	global_load_dwordx4 v[132:135], v[136:137], off
	s_nop 0
	v_addc_co_u32_e32 v149, vcc, 0, v145, vcc
	global_load_dwordx4 v[136:139], v[140:141], off offset:-4096
	s_nop 0
	global_load_dwordx4 v[140:143], v[140:141], off
	s_nop 0
	global_load_dwordx4 v[144:147], v[144:145], off
	s_nop 0
	global_load_dwordx4 v[148:151], v[148:149], off
	s_waitcnt vmcnt(9)
	ds_write_b128 v206, v[112:115]
	s_waitcnt vmcnt(8)
	ds_write_b128 v207, v[116:119]
	s_waitcnt vmcnt(7)
	ds_write_b128 v208, v[120:123]
	s_waitcnt vmcnt(6)
	ds_write_b128 v215, v[124:127]
	s_waitcnt vmcnt(5)
	ds_write_b128 v233, v[128:131]
	v_exp_f32_e32 v48, v48
	v_exp_f32_e32 v49, v49
	v_exp_f32_e32 v50, v50
	v_exp_f32_e32 v51, v51
	s_waitcnt lgkmcnt(13)
	v_mfma_f32_32x32x16_bf16 v[0:15], v[216:219], v[80:83], 0
	ds_read_b128 v[216:219], v153 offset:20000
	v_add_f32_e32 v224, 0, v48
	v_exp_f32_e32 v52, v52
	v_add_f32_e32 v224, v49, v224
	v_cvt_pk_bf16_f32 v188, v48, v49
	s_waitcnt lgkmcnt(13)
	v_mfma_f32_32x32x16_bf16 v[156:171], v[220:223], v[80:83], 0
	ds_read_b128 v[220:223], v153 offset:13376
	v_exp_f32_e32 v53, v53
	v_add_f32_e32 v224, v50, v224
	v_exp_f32_e32 v54, v54
	v_add_f32_e32 v224, v51, v224
	s_waitcnt lgkmcnt(13)
	v_mfma_f32_32x32x16_bf16 v[0:15], v[228:231], v[84:87], v[0:15]
	ds_read_b128 v[228:231], v153 offset:20032
	v_cvt_pk_bf16_f32 v189, v50, v51
	v_exp_f32_e32 v55, v55
	v_add_f32_e32 v224, v52, v224
	v_exp_f32_e32 v56, v56
	s_waitcnt lgkmcnt(2)
	v_mfma_f32_32x32x16_bf16 v[156:171], v[216:219], v[84:87], v[156:171]
	ds_read_b128 v[216:219], v153 offset:13408
	v_add_f32_e32 v224, v53, v224
	v_cvt_pk_bf16_f32 v190, v52, v53
	v_exp_f32_e32 v57, v57
	v_add_f32_e32 v224, v54, v224
	s_waitcnt lgkmcnt(2)
	v_mfma_f32_32x32x16_bf16 v[0:15], v[220:223], v[88:91], v[0:15]
	ds_read_b128 v[220:223], v153 offset:20064
	v_exp_f32_e32 v58, v58
	v_add_f32_e32 v224, v55, v224
	v_cvt_pk_bf16_f32 v191, v54, v55
	v_exp_f32_e32 v59, v59
	s_nop 0
	v_mfma_f32_32x32x16_bf16 v[32:47], v[236:239], v[188:191], v[32:47]
	ds_read_b64_tr_b16 v[236:237], v155 offset:2368
	ds_read_b64_tr_b16 v[238:239], v155 offset:3520
	v_add_f32_e32 v224, v56, v224
	v_exp_f32_e32 v60, v60
	v_add_f32_e32 v224, v57, v224
	v_cvt_pk_bf16_f32 v192, v56, v57
	v_mfma_f32_32x32x16_bf16 v[16:31], v[244:247], v[188:191], v[16:31]
	ds_read_b64_tr_b16 v[244:245], v155 offset:4608
	ds_read_b64_tr_b16 v[246:247], v155 offset:5760
	v_exp_f32_e32 v61, v61
	v_add_f32_e32 v224, v58, v224
	v_exp_f32_e32 v62, v62
	v_add_f32_e32 v224, v59, v224
	s_waitcnt lgkmcnt(6)
	v_mfma_f32_32x32x16_bf16 v[156:171], v[228:231], v[88:91], v[156:171]
	ds_read_b128 v[228:231], v153 offset:13440
	v_cvt_pk_bf16_f32 v193, v58, v59
	v_exp_f32_e32 v63, v63
	v_add_f32_e32 v224, v60, v224
	v_add_f32_e32 v224, v61, v224
	s_waitcnt lgkmcnt(6)
	v_mfma_f32_32x32x16_bf16 v[0:15], v[216:219], v[92:95], v[0:15]
	ds_read_b128 v[216:219], v153 offset:20096
	v_add_f32_e32 v224, v62, v224
	v_add_f32_e32 v224, v63, v224
	v_cvt_pk_bf16_f32 v194, v60, v61
	v_cvt_pk_bf16_f32 v195, v62, v63
	s_waitcnt lgkmcnt(6)
	v_mfma_f32_32x32x16_bf16 v[156:171], v[220:223], v[92:95], v[156:171]
	ds_read_b128 v[220:223], v153 offset:13472
	v_exp_f32_e32 v64, v64
	v_exp_f32_e32 v65, v65
	v_exp_f32_e32 v66, v66
	v_exp_f32_e32 v67, v67
	v_mfma_f32_32x32x16_bf16 v[32:47], v[248:251], v[192:195], v[32:47]
	ds_read_b64_tr_b16 v[248:249], v155 offset:4672
	ds_read_b64_tr_b16 v[250:251], v155 offset:5824
	v_add_f32_e32 v224, v64, v224
	v_exp_f32_e32 v68, v68
	v_add_f32_e32 v224, v65, v224
	v_cvt_pk_bf16_f32 v188, v64, v65
	s_waitcnt lgkmcnt(7)
	v_mfma_f32_32x32x16_bf16 v[16:31], v[236:239], v[192:195], v[16:31]
	ds_read_b64_tr_b16 v[236:237], v155 offset:6912
	ds_read_b64_tr_b16 v[238:239], v155 offset:8064
	v_exp_f32_e32 v69, v69
	v_add_f32_e32 v224, v66, v224
	v_exp_f32_e32 v70, v70
	v_add_f32_e32 v224, v67, v224
	s_waitcnt lgkmcnt(6)
	v_mfma_f32_32x32x16_bf16 v[0:15], v[228:231], v[104:107], v[0:15]
	ds_read_b128 v[228:231], v153 offset:20128
	v_cvt_pk_bf16_f32 v189, v66, v67
	v_exp_f32_e32 v71, v71
	v_add_f32_e32 v224, v68, v224
	v_exp_f32_e32 v72, v72
	s_waitcnt lgkmcnt(6)
	v_mfma_f32_32x32x16_bf16 v[156:171], v[216:219], v[104:107], v[156:171]
	v_add_f32_e32 v224, v69, v224
	v_cvt_pk_bf16_f32 v190, v68, v69
	v_exp_f32_e32 v73, v73
	v_add_f32_e32 v224, v70, v224
	s_waitcnt lgkmcnt(5)
	v_mfma_f32_32x32x16_bf16 v[0:15], v[220:223], v[108:111], v[0:15]
	v_exp_f32_e32 v74, v74
	v_add_f32_e32 v224, v71, v224
	v_cvt_pk_bf16_f32 v191, v70, v71
	v_exp_f32_e32 v75, v75
	s_nop 0
	v_mfma_f32_32x32x16_bf16 v[32:47], v[244:247], v[188:191], v[32:47]
	ds_read_b64_tr_b16 v[244:245], v155 offset:6976
	ds_read_b64_tr_b16 v[246:247], v155 offset:8128
	v_add_f32_e32 v224, v72, v224
	v_exp_f32_e32 v76, v76
	v_add_f32_e32 v224, v73, v224
	v_cvt_pk_bf16_f32 v192, v72, v73
	s_waitcnt lgkmcnt(5)
	v_mfma_f32_32x32x16_bf16 v[16:31], v[248:251], v[188:191], v[16:31]
	v_exp_f32_e32 v77, v77
	v_add_f32_e32 v224, v74, v224
	v_exp_f32_e32 v78, v78
	v_add_f32_e32 v224, v75, v224
	s_waitcnt lgkmcnt(2)
	v_mfma_f32_32x32x16_bf16 v[156:171], v[228:231], v[108:111], v[156:171]
	v_cvt_pk_bf16_f32 v193, v74, v75
	v_exp_f32_e32 v79, v79
	v_add_f32_e32 v224, v76, v224
	v_add_f32_e32 v224, v77, v224
	v_add_f32_e32 v224, v78, v224
	v_add_f32_e32 v224, v79, v224
	v_cvt_pk_bf16_f32 v194, v76, v77
	v_cvt_pk_bf16_f32 v195, v78, v79
	s_nop 1
	v_mfma_f32_32x32x16_bf16 v[32:47], v[236:239], v[192:195], v[32:47]
	s_waitcnt lgkmcnt(0)
	v_mfma_f32_32x32x16_bf16 v[16:31], v[244:247], v[192:195], v[16:31]
	v_add_f32_e32 v152, v152, v224
	s_waitcnt lgkmcnt(0)
	s_barrier
; #define MFMA32(a, b, c) __builtin_amdgcn_mfma_f32_32x32x16_bf16((a), (b), (c), 0, 0, 0)
; DI unsigned pk_bf16(float lo, float hi) { f32x2 v = {lo, hi}; bf2_t b = __builtin_convertvector(v, bf2_t); return __builtin_bit_cast(unsigned, b); }
; template <int DQK, bool SB, bool SMAX>
; DI void attn_item(const Params& p, char* smem, int bh, int qb, float Mb) {
;     ...
;     if (active) {
; #pragma unroll
;       for (int kb = 0; kb < 2; ++kb)
; #pragma unroll
;         for (int i = 0; i < 16; ++i) st[kb][i] = SMAX ? negM[i] : 0.f;
; #pragma unroll
;       for (int ks = 0; ks < NKS; ++ks)
; #pragma unroll
;         for (int kb = 0; kb < 2; ++kb) {
;           const bf16x8 a = *(const bf16x8*)(kc + (kb * 32 + r) * KSTR + ks * 16 + h * 8);
;           st[kb] = MFMA32(a, qf[ks], st[kb]);
;         }
;     }
;     __builtin_amdgcn_sched_barrier(0);
;     AT_WRITE(0, st2 ^ 1)
;     AT_LOAD(0, (it + 2 < nt) ? it + 2 : nt - 1)
;     if (active) {
;       const bool diag = (kb0 + 64 > qw0);
;       bf16x8 pk[4];
;       if (!SB) {
;         if (diag) {
; #pragma unroll
;           for (int kb = 0; kb < 2; ++kb)
; #pragma unroll
;             for (int i = 0; i < 16; ++i) { const int key = kb0 + kb * 32 + crow(i, h); if (key > query) st[kb][i] = -__builtin_huge_valf(); }
;         }
;         if (SMAX) {
;           float ps = 0.f;
; #pragma unroll
;           for (int kb = 0; kb < 2; ++kb)
; #pragma unroll
;             for (int i = 0; i < 16; ++i) { const float pv = fast_exp2(st[kb][i]); st[kb][i] = pv; ps += pv; }
;           lsum += ps;
;     ...
; #pragma unroll
;       for (int kb = 0; kb < 2; ++kb)
; #pragma unroll
;         for (int s = 0; s < 2; ++s) {
;           u32x4 w;
; #pragma unroll
;           for (int e = 0; e < 4; ++e) w[e] = pk_bf16(st[kb][8 * s + 2 * e], st[kb][8 * s + 2 * e + 1]);
;           pk[kb * 2 + s] = __builtin_bit_cast(bf16x8, w);
;         }
; #pragma unroll
;       for (int kk = 0; kk < 4; ++kk)
; #pragma unroll
;         for (int db = 0; db < 2; ++db) {
;           const s16x4 v0 = __builtin_amdgcn_ds_read_tr16_b64_v4i16((lds_s16x4*)(vc + voff + (16 * kk) * VSTR + 32 * db));
;           const s16x4 v1 = __builtin_amdgcn_ds_read_tr16_b64_v4i16((lds_s16x4*)(vc + voff + (16 * kk + 8) * VSTR + 32 * db));
;           const bf16x8 vf = __builtin_shufflevector(v0, v1, 0, 1, 2, 3, 4, 5, 6, 7);
;           O[db] = MFMA32(vf, pk[kk], O[db]);
;         }
	s_mov_b32 s29, s26
	s_mov_b32 s26, s27
	s_mov_b32 s27, s28
	s_mov_b32 s28, s29
	s_add_i32 s14, s14, 1
	v_add_u32_e32 v155, s26, v154
	v_add_u32_e32 v215, s28, v203
	v_add_u32_e32 v233, s28, v204
	ds_read_b128 v[216:219], v153
	ds_read_b128 v[220:223], v153 offset:6656
	ds_read_b128 v[228:231], v153 offset:32
	ds_read_b64_tr_b16 v[236:237], v155
	ds_read_b64_tr_b16 v[238:239], v155 offset:1152
	ds_read_b64_tr_b16 v[244:245], v155 offset:64
	ds_read_b64_tr_b16 v[246:247], v155 offset:1216
	ds_read_b64_tr_b16 v[248:249], v155 offset:2304
	ds_read_b64_tr_b16 v[250:251], v155 offset:3456
	s_min_i32 s2, s14, s4
	s_lshl_b32 s2, s2, 6
	s_ashr_i32 s3, s2, 31
	v_mad_i64_i32 v[116:117], s[18:19], s2, v209, v[182:183]
	v_add_co_u32_e32 v120, vcc, s6, v116
	s_lshl_b64 s[2:3], s[2:3], 7
	s_nop 0
	v_addc_co_u32_e32 v121, vcc, 0, v117, vcc
	v_lshl_add_u64 v[124:125], v[184:185], 0, s[2:3]
	v_add_co_u32_e32 v128, vcc, 0x1000, v124
	global_load_dwordx4 v[112:115], v[116:117], off
	s_nop 0
	v_addc_co_u32_e32 v129, vcc, 0, v125, vcc
	global_load_dwordx4 v[116:119], v[120:121], off offset:-4096
	s_nop 0
	global_load_dwordx4 v[120:123], v[120:121], off
	s_nop 0
	global_load_dwordx4 v[124:127], v[124:125], off
	s_nop 0
	global_load_dwordx4 v[128:131], v[128:129], off
	s_waitcnt vmcnt(9)
	ds_write_b128 v206, v[132:135] offset:13312
	s_waitcnt vmcnt(8)
	ds_write_b128 v207, v[136:139] offset:13312
	s_waitcnt vmcnt(7)
	ds_write_b128 v208, v[140:143] offset:13312
	s_waitcnt vmcnt(6)
	ds_write_b128 v215, v[144:147]
	s_waitcnt vmcnt(5)
	ds_write_b128 v233, v[148:151]
	v_exp_f32_e32 v0, v0
	v_exp_f32_e32 v1, v1
	v_exp_f32_e32 v2, v2
	v_exp_f32_e32 v3, v3
	s_waitcnt lgkmcnt(13)
	v_mfma_f32_32x32x16_bf16 v[48:63], v[216:219], v[80:83], 0
	ds_read_b128 v[216:219], v153 offset:6688
	v_add_f32_e32 v224, 0, v0
	v_exp_f32_e32 v4, v4
	v_add_f32_e32 v224, v1, v224
	v_cvt_pk_bf16_f32 v188, v0, v1
	s_waitcnt lgkmcnt(13)
	v_mfma_f32_32x32x16_bf16 v[64:79], v[220:223], v[80:83], 0
	ds_read_b128 v[220:223], v153 offset:64
	v_exp_f32_e32 v5, v5
	v_add_f32_e32 v224, v2, v224
	v_exp_f32_e32 v6, v6
	v_add_f32_e32 v224, v3, v224
	s_waitcnt lgkmcnt(13)
	v_mfma_f32_32x32x16_bf16 v[48:63], v[228:231], v[84:87], v[48:63]
	ds_read_b128 v[228:231], v153 offset:6720
	v_cvt_pk_bf16_f32 v189, v2, v3
	v_exp_f32_e32 v7, v7
	v_add_f32_e32 v224, v4, v224
	v_exp_f32_e32 v8, v8
	s_waitcnt lgkmcnt(2)
	v_mfma_f32_32x32x16_bf16 v[64:79], v[216:219], v[84:87], v[64:79]
	ds_read_b128 v[216:219], v153 offset:96
	v_add_f32_e32 v224, v5, v224
	v_cvt_pk_bf16_f32 v190, v4, v5
	v_exp_f32_e32 v9, v9
	v_add_f32_e32 v224, v6, v224
	s_waitcnt lgkmcnt(2)
	v_mfma_f32_32x32x16_bf16 v[48:63], v[220:223], v[88:91], v[48:63]
	ds_read_b128 v[220:223], v153 offset:6752
	v_exp_f32_e32 v10, v10
	v_add_f32_e32 v224, v7, v224
	v_cvt_pk_bf16_f32 v191, v6, v7
	v_exp_f32_e32 v11, v11
	s_nop 0
	v_mfma_f32_32x32x16_bf16 v[32:47], v[236:239], v[188:191], v[32:47]
	ds_read_b64_tr_b16 v[236:237], v155 offset:2368
	ds_read_b64_tr_b16 v[238:239], v155 offset:3520
	v_add_f32_e32 v224, v8, v224
	v_exp_f32_e32 v12, v12
	v_add_f32_e32 v224, v9, v224
	v_cvt_pk_bf16_f32 v192, v8, v9
	v_mfma_f32_32x32x16_bf16 v[16:31], v[244:247], v[188:191], v[16:31]
	ds_read_b64_tr_b16 v[244:245], v155 offset:4608
	ds_read_b64_tr_b16 v[246:247], v155 offset:5760
	v_exp_f32_e32 v13, v13
	v_add_f32_e32 v224, v10, v224
	v_exp_f32_e32 v14, v14
	v_add_f32_e32 v224, v11, v224
	s_waitcnt lgkmcnt(6)
	v_mfma_f32_32x32x16_bf16 v[64:79], v[228:231], v[88:91], v[64:79]
	ds_read_b128 v[228:231], v153 offset:128
	v_cvt_pk_bf16_f32 v193, v10, v11
	v_exp_f32_e32 v15, v15
	v_add_f32_e32 v224, v12, v224
	v_add_f32_e32 v224, v13, v224
	s_waitcnt lgkmcnt(6)
	v_mfma_f32_32x32x16_bf16 v[48:63], v[216:219], v[92:95], v[48:63]
	ds_read_b128 v[216:219], v153 offset:6784
	v_add_f32_e32 v224, v14, v224
	v_add_f32_e32 v224, v15, v224
	v_cvt_pk_bf16_f32 v194, v12, v13
	v_cvt_pk_bf16_f32 v195, v14, v15
	s_waitcnt lgkmcnt(6)
	v_mfma_f32_32x32x16_bf16 v[64:79], v[220:223], v[92:95], v[64:79]
	ds_read_b128 v[220:223], v153 offset:160
	v_exp_f32_e32 v156, v156
	v_exp_f32_e32 v157, v157
	v_exp_f32_e32 v158, v158
	v_exp_f32_e32 v159, v159
	v_mfma_f32_32x32x16_bf16 v[32:47], v[248:251], v[192:195], v[32:47]
	ds_read_b64_tr_b16 v[248:249], v155 offset:4672
	ds_read_b64_tr_b16 v[250:251], v155 offset:5824
	v_add_f32_e32 v224, v156, v224
	v_exp_f32_e32 v160, v160
	v_add_f32_e32 v224, v157, v224
	v_cvt_pk_bf16_f32 v188, v156, v157
	s_waitcnt lgkmcnt(7)
	v_mfma_f32_32x32x16_bf16 v[16:31], v[236:239], v[192:195], v[16:31]
	ds_read_b64_tr_b16 v[236:237], v155 offset:6912
	ds_read_b64_tr_b16 v[238:239], v155 offset:8064
	v_exp_f32_e32 v161, v161
	v_add_f32_e32 v224, v158, v224
	v_exp_f32_e32 v162, v162
	v_add_f32_e32 v224, v159, v224
	s_waitcnt lgkmcnt(6)
	v_mfma_f32_32x32x16_bf16 v[48:63], v[228:231], v[104:107], v[48:63]
	ds_read_b128 v[228:231], v153 offset:6816
	v_cvt_pk_bf16_f32 v189, v158, v159
	v_exp_f32_e32 v163, v163
	v_add_f32_e32 v224, v160, v224
	v_exp_f32_e32 v164, v164
	s_waitcnt lgkmcnt(6)
	v_mfma_f32_32x32x16_bf16 v[64:79], v[216:219], v[104:107], v[64:79]
	v_add_f32_e32 v224, v161, v224
	v_cvt_pk_bf16_f32 v190, v160, v161
	v_exp_f32_e32 v165, v165
	v_add_f32_e32 v224, v162, v224
	s_waitcnt lgkmcnt(5)
	v_mfma_f32_32x32x16_bf16 v[48:63], v[220:223], v[108:111], v[48:63]
	v_exp_f32_e32 v166, v166
	v_add_f32_e32 v224, v163, v224
	v_cvt_pk_bf16_f32 v191, v162, v163
	v_exp_f32_e32 v167, v167
	s_nop 0
	v_mfma_f32_32x32x16_bf16 v[32:47], v[244:247], v[188:191], v[32:47]
	ds_read_b64_tr_b16 v[244:245], v155 offset:6976
	ds_read_b64_tr_b16 v[246:247], v155 offset:8128
	v_add_f32_e32 v224, v164, v224
	v_exp_f32_e32 v168, v168
	v_add_f32_e32 v224, v165, v224
	v_cvt_pk_bf16_f32 v192, v164, v165
	s_waitcnt lgkmcnt(5)
	v_mfma_f32_32x32x16_bf16 v[16:31], v[248:251], v[188:191], v[16:31]
	v_exp_f32_e32 v169, v169
	v_add_f32_e32 v224, v166, v224
	v_exp_f32_e32 v170, v170
	v_add_f32_e32 v224, v167, v224
	s_waitcnt lgkmcnt(2)
	v_mfma_f32_32x32x16_bf16 v[64:79], v[228:231], v[108:111], v[64:79]
	v_cvt_pk_bf16_f32 v193, v166, v167
	v_exp_f32_e32 v171, v171
	v_add_f32_e32 v224, v168, v224
	v_add_f32_e32 v224, v169, v224
	v_add_f32_e32 v224, v170, v224
	v_add_f32_e32 v224, v171, v224
	v_cvt_pk_bf16_f32 v194, v168, v169
	v_cvt_pk_bf16_f32 v195, v170, v171
	s_nop 1
	v_mfma_f32_32x32x16_bf16 v[32:47], v[236:239], v[192:195], v[32:47]
	s_waitcnt lgkmcnt(0)
	v_mfma_f32_32x32x16_bf16 v[16:31], v[244:247], v[192:195], v[16:31]
	v_add_f32_e32 v152, v152, v224
	s_waitcnt lgkmcnt(0)
	s_barrier
	s_mov_b32 s29, s26
	s_mov_b32 s26, s27
	s_mov_b32 s27, s28
	s_mov_b32 s28, s29
	s_add_i32 s14, s14, 1
	s_add_i32 s21, s21, -1
	s_cmp_lg_u32 s21, 0
	s_cbranch_scc1 .Lt15_loop
; #define MFMA32(a, b, c) __builtin_amdgcn_mfma_f32_32x32x16_bf16((a), (b), (c), 0, 0, 0)
; DI int crow(int i, int h) { return (i & 3) + 8 * (i >> 2) + 4 * h; }
; #define AT_LOAD(SET, IT) { const int kl_ = AT_KB(IT); \
;     _Pragma("unroll") for (int i = 0; i < KPT; ++i) kreg[SET][i] = *(const u32x4*)(Kg + (size_t)kl_ * DQK + (tid + 256 * i) * 8); \
;     _Pragma("unroll") for (int i = 0; i < 2; ++i) vreg[SET][i] = *(const u32x4*)(Vg + (size_t)kl_ * 64 + (tid + 256 * i) * 8); \
;     __builtin_amdgcn_sched_barrier(0); }
; #define AT_WRITE(SET, BUFI) { \
;     _Pragma("unroll") for (int i = 0; i < KPT; ++i) { const int c = tid + 256 * i, row = c / KCH, kcol = c % KCH; *(u32x4*)(Ks + (BUFI) * KBUF + row * KSTR + kcol * 8) = kreg[SET][i]; } \
;     _Pragma("unroll") for (int i = 0; i < 2; ++i) { const int c = tid + 256 * i; *(u32x4*)(Vs + (BUFI) * VBUF + (c >> 3) * VSTR + (c & 7) * 8) = vreg[SET][i]; } }
; template <int DQK, bool SB, bool SMAX>
; DI void attn_item(const Params& p, char* smem, int bh, int qb, float Mb) {
;     ...
;     if (active) {
; #pragma unroll
;       for (int kb = 0; kb < 2; ++kb)
; #pragma unroll
;         for (int i = 0; i < 16; ++i) st[kb][i] = SMAX ? negM[i] : 0.f;
; #pragma unroll
;       for (int ks = 0; ks < NKS; ++ks)
; #pragma unroll
;         for (int kb = 0; kb < 2; ++kb) {
;           const bf16x8 a = *(const bf16x8*)(kc + (kb * 32 + r) * KSTR + ks * 16 + h * 8);
;           st[kb] = MFMA32(a, qf[ks], st[kb]);
;         }
;     }
;     __builtin_amdgcn_sched_barrier(0);
;     AT_WRITE(0, st2 ^ 1)
;     AT_LOAD(0, (it + 2 < nt) ? it + 2 : nt - 1)
;     if (active) {
;       const bool diag = (kb0 + 64 > qw0);
;       bf16x8 pk[4];
;       if (!SB) {
;         if (diag) {
; #pragma unroll
;           for (int kb = 0; kb < 2; ++kb)
; #pragma unroll
;             for (int i = 0; i < 16; ++i) { const int key = kb0 + kb * 32 + crow(i, h); if (key > query) st[kb][i] = -__builtin_huge_valf(); }
.Lt15_tail:
	v_add_u32_e32 v155, s26, v154
	v_add_u32_e32 v215, s28, v203
	v_add_u32_e32 v233, s28, v204
	ds_read_b128 v[216:219], v153 offset:13312
	ds_read_b128 v[220:223], v153 offset:19968
	ds_read_b128 v[228:231], v153 offset:13344
	s_min_i32 s2, s14, s4
	s_lshl_b32 s2, s2, 6
	s_ashr_i32 s3, s2, 31
	v_mad_i64_i32 v[136:137], s[18:19], s2, v209, v[182:183]
	v_add_co_u32_e32 v140, vcc, s6, v136
	s_lshl_b64 s[2:3], s[2:3], 7
	s_nop 0
	v_addc_co_u32_e32 v141, vcc, 0, v137, vcc
	v_lshl_add_u64 v[144:145], v[184:185], 0, s[2:3]
	v_add_co_u32_e32 v148, vcc, 0x1000, v144
	global_load_dwordx4 v[132:135], v[136:137], off
	s_nop 0
	v_addc_co_u32_e32 v149, vcc, 0, v145, vcc
	global_load_dwordx4 v[136:139], v[140:141], off offset:-4096
	s_nop 0
	global_load_dwordx4 v[140:143], v[140:141], off
	s_nop 0
	global_load_dwordx4 v[144:147], v[144:145], off
	s_nop 0
	global_load_dwordx4 v[148:151], v[148:149], off
	s_waitcnt vmcnt(9)
	ds_write_b128 v206, v[112:115]
	s_waitcnt vmcnt(8)
	ds_write_b128 v207, v[116:119]
	s_waitcnt vmcnt(7)
	ds_write_b128 v208, v[120:123]
	s_waitcnt vmcnt(6)
	ds_write_b128 v215, v[124:127]
	s_waitcnt vmcnt(5)
	ds_write_b128 v233, v[128:131]
	s_waitcnt lgkmcnt(7)
	v_mfma_f32_32x32x16_bf16 v[0:15], v[216:219], v[80:83], 0
	ds_read_b128 v[216:219], v153 offset:20000
	s_waitcnt lgkmcnt(7)
	v_mfma_f32_32x32x16_bf16 v[156:171], v[220:223], v[80:83], 0
	ds_read_b128 v[220:223], v153 offset:13376
	s_waitcnt lgkmcnt(7)
	v_mfma_f32_32x32x16_bf16 v[0:15], v[228:231], v[84:87], v[0:15]
	ds_read_b128 v[228:231], v153 offset:20032
	s_waitcnt lgkmcnt(2)
	v_mfma_f32_32x32x16_bf16 v[156:171], v[216:219], v[84:87], v[156:171]
	ds_read_b128 v[216:219], v153 offset:13408
	s_waitcnt lgkmcnt(2)
	v_mfma_f32_32x32x16_bf16 v[0:15], v[220:223], v[88:91], v[0:15]
	ds_read_b128 v[220:223], v153 offset:20064
	s_waitcnt lgkmcnt(2)
	v_mfma_f32_32x32x16_bf16 v[156:171], v[228:231], v[88:91], v[156:171]
	ds_read_b128 v[228:231], v153 offset:13440
	s_waitcnt lgkmcnt(2)
	v_mfma_f32_32x32x16_bf16 v[0:15], v[216:219], v[92:95], v[0:15]
	ds_read_b128 v[216:219], v153 offset:20096
	s_waitcnt lgkmcnt(2)
	v_mfma_f32_32x32x16_bf16 v[156:171], v[220:223], v[92:95], v[156:171]
	ds_read_b128 v[220:223], v153 offset:13472
	s_waitcnt lgkmcnt(2)
	v_mfma_f32_32x32x16_bf16 v[0:15], v[228:231], v[104:107], v[0:15]
	ds_read_b128 v[228:231], v153 offset:20128
	s_waitcnt lgkmcnt(2)
	v_mfma_f32_32x32x16_bf16 v[156:171], v[216:219], v[104:107], v[156:171]
	s_waitcnt lgkmcnt(1)
	v_mfma_f32_32x32x16_bf16 v[0:15], v[220:223], v[108:111], v[0:15]
	s_waitcnt lgkmcnt(0)
	v_mfma_f32_32x32x16_bf16 v[156:171], v[228:231], v[108:111], v[156:171]
	s_lshl_b32 s2, s1, 6
	s_add_i32 s2, s2, 0xffffff80
	s_nop 7
	s_nop 3
	v_add_u32_e32 v227, s2, v197
	v_add_u32_e32 v225, 0, v227
	v_cmp_le_u32_e32 vcc, v225, v176
	s_nop 1
	v_cndmask_b32_e32 v48, v210, v48, vcc
	v_add_u32_e32 v225, 1, v227
	v_cmp_le_u32_e32 vcc, v225, v176
	s_nop 1
	v_cndmask_b32_e32 v49, v210, v49, vcc
	v_add_u32_e32 v225, 2, v227
	v_cmp_le_u32_e32 vcc, v225, v176
	s_nop 1
	v_cndmask_b32_e32 v50, v210, v50, vcc
	v_add_u32_e32 v225, 3, v227
	v_cmp_le_u32_e32 vcc, v225, v176
	s_nop 1
	v_cndmask_b32_e32 v51, v210, v51, vcc
	v_add_u32_e32 v225, 8, v227
	v_cmp_le_u32_e32 vcc, v225, v176
	s_nop 1
	v_cndmask_b32_e32 v52, v210, v52, vcc
	v_add_u32_e32 v225, 9, v227
	v_cmp_le_u32_e32 vcc, v225, v176
	s_nop 1
	v_cndmask_b32_e32 v53, v210, v53, vcc
	v_add_u32_e32 v225, 10, v227
	v_cmp_le_u32_e32 vcc, v225, v176
	s_nop 1
	v_cndmask_b32_e32 v54, v210, v54, vcc
	v_add_u32_e32 v225, 11, v227
	v_cmp_le_u32_e32 vcc, v225, v176
	s_nop 1
	v_cndmask_b32_e32 v55, v210, v55, vcc
	v_add_u32_e32 v225, 16, v227
	v_cmp_le_u32_e32 vcc, v225, v176
	s_nop 1
	v_cndmask_b32_e32 v56, v210, v56, vcc
	v_add_u32_e32 v225, 17, v227
	v_cmp_le_u32_e32 vcc, v225, v176
	s_nop 1
	v_cndmask_b32_e32 v57, v210, v57, vcc
	v_add_u32_e32 v225, 18, v227
	v_cmp_le_u32_e32 vcc, v225, v176
	s_nop 1
	v_cndmask_b32_e32 v58, v210, v58, vcc
	v_add_u32_e32 v225, 19, v227
	v_cmp_le_u32_e32 vcc, v225, v176
	s_nop 1
	v_cndmask_b32_e32 v59, v210, v59, vcc
	v_add_u32_e32 v225, 24, v227
	v_cmp_le_u32_e32 vcc, v225, v176
	s_nop 1
	v_cndmask_b32_e32 v60, v210, v60, vcc
	v_add_u32_e32 v225, 25, v227
	v_cmp_le_u32_e32 vcc, v225, v176
	s_nop 1
	v_cndmask_b32_e32 v61, v210, v61, vcc
	v_add_u32_e32 v225, 26, v227
	v_cmp_le_u32_e32 vcc, v225, v176
	s_nop 1
	v_cndmask_b32_e32 v62, v210, v62, vcc
	v_add_u32_e32 v225, 27, v227
	v_cmp_le_u32_e32 vcc, v225, v176
	s_nop 1
	v_cndmask_b32_e32 v63, v210, v63, vcc
	v_add_u32_e32 v225, 32, v227
	v_cmp_le_u32_e32 vcc, v225, v176
	s_nop 1
	v_cndmask_b32_e32 v64, v210, v64, vcc
	v_add_u32_e32 v225, 33, v227
	v_cmp_le_u32_e32 vcc, v225, v176
	s_nop 1
	v_cndmask_b32_e32 v65, v210, v65, vcc
	v_add_u32_e32 v225, 34, v227
	v_cmp_le_u32_e32 vcc, v225, v176
	s_nop 1
	v_cndmask_b32_e32 v66, v210, v66, vcc
	v_add_u32_e32 v225, 35, v227
	v_cmp_le_u32_e32 vcc, v225, v176
	s_nop 1
	v_cndmask_b32_e32 v67, v210, v67, vcc
	v_add_u32_e32 v225, 40, v227
	v_cmp_le_u32_e32 vcc, v225, v176
	s_nop 1
	v_cndmask_b32_e32 v68, v210, v68, vcc
	v_add_u32_e32 v225, 41, v227
	v_cmp_le_u32_e32 vcc, v225, v176
	s_nop 1
	v_cndmask_b32_e32 v69, v210, v69, vcc
	v_add_u32_e32 v225, 42, v227
	v_cmp_le_u32_e32 vcc, v225, v176
	s_nop 1
	v_cndmask_b32_e32 v70, v210, v70, vcc
	v_add_u32_e32 v225, 43, v227
	v_cmp_le_u32_e32 vcc, v225, v176
	s_nop 1
	v_cndmask_b32_e32 v71, v210, v71, vcc
	v_add_u32_e32 v225, 48, v227
	v_cmp_le_u32_e32 vcc, v225, v176
	s_nop 1
	v_cndmask_b32_e32 v72, v210, v72, vcc
	v_add_u32_e32 v225, 49, v227
	v_cmp_le_u32_e32 vcc, v225, v176
	s_nop 1
	v_cndmask_b32_e32 v73, v210, v73, vcc
; #define MFMA32(a, b, c) __builtin_amdgcn_mfma_f32_32x32x16_bf16((a), (b), (c), 0, 0, 0)
; DI unsigned pk_bf16(float lo, float hi) { f32x2 v = {lo, hi}; bf2_t b = __builtin_convertvector(v, bf2_t); return __builtin_bit_cast(unsigned, b); }
; DI int crow(int i, int h) { return (i & 3) + 8 * (i >> 2) + 4 * h; }
; DI float fast_exp2(float x) { return __builtin_amdgcn_exp2f(x); }
; template <int DQK, bool SB, bool SMAX>
; DI void attn_item(const Params& p, char* smem, int bh, int qb, float Mb) {
;     ...
;             for (int i = 0; i < 16; ++i) { const int key = kb0 + kb * 32 + crow(i, h); if (key > query) st[kb][i] = -__builtin_huge_valf(); }
;         }
;         if (SMAX) {
;           float ps = 0.f;
; #pragma unroll
;           for (int kb = 0; kb < 2; ++kb)
; #pragma unroll
;             for (int i = 0; i < 16; ++i) { const float pv = fast_exp2(st[kb][i]); st[kb][i] = pv; ps += pv; }
;           lsum += ps;
;     ...
; #pragma unroll
;       for (int kb = 0; kb < 2; ++kb)
; #pragma unroll
;         for (int s = 0; s < 2; ++s) {
;           u32x4 w;
; #pragma unroll
;           for (int e = 0; e < 4; ++e) w[e] = pk_bf16(st[kb][8 * s + 2 * e], st[kb][8 * s + 2 * e + 1]);
;           pk[kb * 2 + s] = __builtin_bit_cast(bf16x8, w);
;         }
; #pragma unroll
;       for (int kk = 0; kk < 4; ++kk)
; #pragma unroll
;         for (int db = 0; db < 2; ++db) {
;           const s16x4 v0 = __builtin_amdgcn_ds_read_tr16_b64_v4i16((lds_s16x4*)(vc + voff + (16 * kk) * VSTR + 32 * db));
;           const s16x4 v1 = __builtin_amdgcn_ds_read_tr16_b64_v4i16((lds_s16x4*)(vc + voff + (16 * kk + 8) * VSTR + 32 * db));
;           const bf16x8 vf = __builtin_shufflevector(v0, v1, 0, 1, 2, 3, 4, 5, 6, 7);
;           O[db] = MFMA32(vf, pk[kk], O[db]);
;         }
	v_add_u32_e32 v225, 50, v227
	v_cmp_le_u32_e32 vcc, v225, v176
	s_nop 1
	v_cndmask_b32_e32 v74, v210, v74, vcc
	v_add_u32_e32 v225, 51, v227
	v_cmp_le_u32_e32 vcc, v225, v176
	s_nop 1
	v_cndmask_b32_e32 v75, v210, v75, vcc
	v_add_u32_e32 v225, 56, v227
	v_cmp_le_u32_e32 vcc, v225, v176
	s_nop 1
	v_cndmask_b32_e32 v76, v210, v76, vcc
	v_add_u32_e32 v225, 57, v227
	v_cmp_le_u32_e32 vcc, v225, v176
	s_nop 1
	v_cndmask_b32_e32 v77, v210, v77, vcc
	v_add_u32_e32 v225, 58, v227
	v_cmp_le_u32_e32 vcc, v225, v176
	s_nop 1
	v_cndmask_b32_e32 v78, v210, v78, vcc
	v_add_u32_e32 v225, 59, v227
	v_cmp_le_u32_e32 vcc, v225, v176
	s_nop 1
	v_cndmask_b32_e32 v79, v210, v79, vcc
	ds_read_b64_tr_b16 v[236:237], v155
	ds_read_b64_tr_b16 v[238:239], v155 offset:1152
	ds_read_b64_tr_b16 v[244:245], v155 offset:64
	ds_read_b64_tr_b16 v[246:247], v155 offset:1216
	ds_read_b64_tr_b16 v[248:249], v155 offset:2304
	ds_read_b64_tr_b16 v[250:251], v155 offset:3456
	v_exp_f32_e32 v48, v48
	v_exp_f32_e32 v49, v49
	v_exp_f32_e32 v50, v50
	v_exp_f32_e32 v51, v51
	v_add_f32_e32 v224, 0, v48
	v_exp_f32_e32 v52, v52
	v_add_f32_e32 v224, v49, v224
	v_cvt_pk_bf16_f32 v188, v48, v49
	v_exp_f32_e32 v53, v53
	v_add_f32_e32 v224, v50, v224
	v_exp_f32_e32 v54, v54
	v_add_f32_e32 v224, v51, v224
	v_cvt_pk_bf16_f32 v189, v50, v51
	v_exp_f32_e32 v55, v55
	v_add_f32_e32 v224, v52, v224
	v_exp_f32_e32 v56, v56
	v_add_f32_e32 v224, v53, v224
	v_cvt_pk_bf16_f32 v190, v52, v53
	v_exp_f32_e32 v57, v57
	v_add_f32_e32 v224, v54, v224
	v_exp_f32_e32 v58, v58
	v_add_f32_e32 v224, v55, v224
	v_cvt_pk_bf16_f32 v191, v54, v55
	v_exp_f32_e32 v59, v59
	v_add_f32_e32 v224, v56, v224
	v_exp_f32_e32 v60, v60
	v_add_f32_e32 v224, v57, v224
	v_cvt_pk_bf16_f32 v192, v56, v57
	v_exp_f32_e32 v61, v61
	v_add_f32_e32 v224, v58, v224
	v_exp_f32_e32 v62, v62
	v_add_f32_e32 v224, v59, v224
	v_cvt_pk_bf16_f32 v193, v58, v59
	v_exp_f32_e32 v63, v63
	v_add_f32_e32 v224, v60, v224
	v_add_f32_e32 v224, v61, v224
	v_add_f32_e32 v224, v62, v224
	v_add_f32_e32 v224, v63, v224
	v_cvt_pk_bf16_f32 v194, v60, v61
	v_cvt_pk_bf16_f32 v195, v62, v63
	s_nop 1
	s_waitcnt lgkmcnt(4)
	v_mfma_f32_32x32x16_bf16 v[32:47], v[236:239], v[188:191], v[32:47]
	ds_read_b64_tr_b16 v[236:237], v155 offset:2368
	ds_read_b64_tr_b16 v[238:239], v155 offset:3520
	s_waitcnt lgkmcnt(4)
	v_mfma_f32_32x32x16_bf16 v[16:31], v[244:247], v[188:191], v[16:31]
	ds_read_b64_tr_b16 v[244:245], v155 offset:4608
	ds_read_b64_tr_b16 v[246:247], v155 offset:5760
	s_waitcnt lgkmcnt(4)
	v_mfma_f32_32x32x16_bf16 v[32:47], v[248:251], v[192:195], v[32:47]
	ds_read_b64_tr_b16 v[248:249], v155 offset:4672
	ds_read_b64_tr_b16 v[250:251], v155 offset:5824
	s_waitcnt lgkmcnt(4)
	v_mfma_f32_32x32x16_bf16 v[16:31], v[236:239], v[192:195], v[16:31]
	ds_read_b64_tr_b16 v[236:237], v155 offset:6912
	ds_read_b64_tr_b16 v[238:239], v155 offset:8064
	v_exp_f32_e32 v64, v64
	v_exp_f32_e32 v65, v65
	v_exp_f32_e32 v66, v66
	v_exp_f32_e32 v67, v67
	v_add_f32_e32 v224, v64, v224
	v_exp_f32_e32 v68, v68
	v_add_f32_e32 v224, v65, v224
	v_cvt_pk_bf16_f32 v188, v64, v65
	v_exp_f32_e32 v69, v69
	v_add_f32_e32 v224, v66, v224
	v_exp_f32_e32 v70, v70
	v_add_f32_e32 v224, v67, v224
	v_cvt_pk_bf16_f32 v189, v66, v67
	v_exp_f32_e32 v71, v71
	v_add_f32_e32 v224, v68, v224
	v_exp_f32_e32 v72, v72
	v_add_f32_e32 v224, v69, v224
	v_cvt_pk_bf16_f32 v190, v68, v69
	v_exp_f32_e32 v73, v73
	v_add_f32_e32 v224, v70, v224
	v_exp_f32_e32 v74, v74
	v_add_f32_e32 v224, v71, v224
	v_cvt_pk_bf16_f32 v191, v70, v71
	v_exp_f32_e32 v75, v75
	v_add_f32_e32 v224, v72, v224
	v_exp_f32_e32 v76, v76
	v_add_f32_e32 v224, v73, v224
	v_cvt_pk_bf16_f32 v192, v72, v73
	v_exp_f32_e32 v77, v77
	v_add_f32_e32 v224, v74, v224
	v_exp_f32_e32 v78, v78
	v_add_f32_e32 v224, v75, v224
	v_cvt_pk_bf16_f32 v193, v74, v75
	v_exp_f32_e32 v79, v79
	v_add_f32_e32 v224, v76, v224
	v_add_f32_e32 v224, v77, v224
	v_add_f32_e32 v224, v78, v224
	v_add_f32_e32 v224, v79, v224
	v_cvt_pk_bf16_f32 v194, v76, v77
	v_cvt_pk_bf16_f32 v195, v78, v79
	s_nop 1
	s_waitcnt lgkmcnt(4)
	v_mfma_f32_32x32x16_bf16 v[32:47], v[244:247], v[188:191], v[32:47]
	ds_read_b64_tr_b16 v[244:245], v155 offset:6976
	ds_read_b64_tr_b16 v[246:247], v155 offset:8128
	s_waitcnt lgkmcnt(4)
	v_mfma_f32_32x32x16_bf16 v[16:31], v[248:251], v[188:191], v[16:31]
	s_waitcnt lgkmcnt(2)
	v_mfma_f32_32x32x16_bf16 v[32:47], v[236:239], v[192:195], v[32:47]
	s_waitcnt lgkmcnt(0)
	v_mfma_f32_32x32x16_bf16 v[16:31], v[244:247], v[192:195], v[16:31]
	v_add_f32_e32 v152, v152, v224
	s_waitcnt lgkmcnt(0)
	s_barrier
	s_mov_b32 s29, s26
	s_mov_b32 s26, s27
	s_mov_b32 s27, s28
	s_mov_b32 s28, s29
	s_add_i32 s14, s14, 1
	s_lshl_b32 s2, s4, 6
	s_cmp_gt_u32 s2, s20
	s_cbranch_scc1 .Lt15_done
; DI int crow(int i, int h) { return (i & 3) + 8 * (i >> 2) + 4 * h; }
; DI float fast_exp2(float x) { return __builtin_amdgcn_exp2f(x); }
; template <int DQK, bool SB, bool SMAX>
; DI void attn_item(const Params& p, char* smem, int bh, int qb, float Mb) {
;     ...
;         if (diag) {
; #pragma unroll
;           for (int kb = 0; kb < 2; ++kb)
; #pragma unroll
;             for (int i = 0; i < 16; ++i) { const int key = kb0 + kb * 32 + crow(i, h); if (key > query) st[kb][i] = -__builtin_huge_valf(); }
;         }
;         if (SMAX) {
;           float ps = 0.f;
; #pragma unroll
;           for (int kb = 0; kb < 2; ++kb)
; #pragma unroll
;             for (int i = 0; i < 16; ++i) { const float pv = fast_exp2(st[kb][i]); st[kb][i] = pv; ps += pv; }
;           lsum += ps;
	v_add_u32_e32 v155, s26, v154
	v_add_u32_e32 v227, s2, v197
	v_add_u32_e32 v225, 0, v227
	v_cmp_le_u32_e32 vcc, v225, v176
	s_nop 1
	v_cndmask_b32_e32 v0, v210, v0, vcc
	v_add_u32_e32 v225, 1, v227
	v_cmp_le_u32_e32 vcc, v225, v176
	s_nop 1
	v_cndmask_b32_e32 v1, v210, v1, vcc
	v_add_u32_e32 v225, 2, v227
	v_cmp_le_u32_e32 vcc, v225, v176
	s_nop 1
	v_cndmask_b32_e32 v2, v210, v2, vcc
	v_add_u32_e32 v225, 3, v227
	v_cmp_le_u32_e32 vcc, v225, v176
	s_nop 1
	v_cndmask_b32_e32 v3, v210, v3, vcc
	v_add_u32_e32 v225, 8, v227
	v_cmp_le_u32_e32 vcc, v225, v176
	s_nop 1
	v_cndmask_b32_e32 v4, v210, v4, vcc
	v_add_u32_e32 v225, 9, v227
	v_cmp_le_u32_e32 vcc, v225, v176
	s_nop 1
	v_cndmask_b32_e32 v5, v210, v5, vcc
	v_add_u32_e32 v225, 10, v227
	v_cmp_le_u32_e32 vcc, v225, v176
	s_nop 1
	v_cndmask_b32_e32 v6, v210, v6, vcc
	v_add_u32_e32 v225, 11, v227
	v_cmp_le_u32_e32 vcc, v225, v176
	s_nop 1
	v_cndmask_b32_e32 v7, v210, v7, vcc
	v_add_u32_e32 v225, 16, v227
	v_cmp_le_u32_e32 vcc, v225, v176
	s_nop 1
	v_cndmask_b32_e32 v8, v210, v8, vcc
	v_add_u32_e32 v225, 17, v227
	v_cmp_le_u32_e32 vcc, v225, v176
	s_nop 1
	v_cndmask_b32_e32 v9, v210, v9, vcc
	v_add_u32_e32 v225, 18, v227
	v_cmp_le_u32_e32 vcc, v225, v176
	s_nop 1
	v_cndmask_b32_e32 v10, v210, v10, vcc
	v_add_u32_e32 v225, 19, v227
	v_cmp_le_u32_e32 vcc, v225, v176
	s_nop 1
	v_cndmask_b32_e32 v11, v210, v11, vcc
	v_add_u32_e32 v225, 24, v227
	v_cmp_le_u32_e32 vcc, v225, v176
	s_nop 1
	v_cndmask_b32_e32 v12, v210, v12, vcc
	v_add_u32_e32 v225, 25, v227
	v_cmp_le_u32_e32 vcc, v225, v176
	s_nop 1
	v_cndmask_b32_e32 v13, v210, v13, vcc
	v_add_u32_e32 v225, 26, v227
	v_cmp_le_u32_e32 vcc, v225, v176
	s_nop 1
	v_cndmask_b32_e32 v14, v210, v14, vcc
	v_add_u32_e32 v225, 27, v227
	v_cmp_le_u32_e32 vcc, v225, v176
	s_nop 1
	v_cndmask_b32_e32 v15, v210, v15, vcc
	v_add_u32_e32 v225, 32, v227
	v_cmp_le_u32_e32 vcc, v225, v176
	s_nop 1
	v_cndmask_b32_e32 v156, v210, v156, vcc
	v_add_u32_e32 v225, 33, v227
	v_cmp_le_u32_e32 vcc, v225, v176
	s_nop 1
	v_cndmask_b32_e32 v157, v210, v157, vcc
	v_add_u32_e32 v225, 34, v227
	v_cmp_le_u32_e32 vcc, v225, v176
	s_nop 1
	v_cndmask_b32_e32 v158, v210, v158, vcc
	v_add_u32_e32 v225, 35, v227
	v_cmp_le_u32_e32 vcc, v225, v176
	s_nop 1
	v_cndmask_b32_e32 v159, v210, v159, vcc
	v_add_u32_e32 v225, 40, v227
	v_cmp_le_u32_e32 vcc, v225, v176
	s_nop 1
	v_cndmask_b32_e32 v160, v210, v160, vcc
	v_add_u32_e32 v225, 41, v227
	v_cmp_le_u32_e32 vcc, v225, v176
	s_nop 1
	v_cndmask_b32_e32 v161, v210, v161, vcc
	v_add_u32_e32 v225, 42, v227
	v_cmp_le_u32_e32 vcc, v225, v176
	s_nop 1
	v_cndmask_b32_e32 v162, v210, v162, vcc
	v_add_u32_e32 v225, 43, v227
	v_cmp_le_u32_e32 vcc, v225, v176
	s_nop 1
	v_cndmask_b32_e32 v163, v210, v163, vcc
	v_add_u32_e32 v225, 48, v227
	v_cmp_le_u32_e32 vcc, v225, v176
	s_nop 1
	v_cndmask_b32_e32 v164, v210, v164, vcc
	v_add_u32_e32 v225, 49, v227
	v_cmp_le_u32_e32 vcc, v225, v176
	s_nop 1
	v_cndmask_b32_e32 v165, v210, v165, vcc
	v_add_u32_e32 v225, 50, v227
	v_cmp_le_u32_e32 vcc, v225, v176
	s_nop 1
	v_cndmask_b32_e32 v166, v210, v166, vcc
	v_add_u32_e32 v225, 51, v227
	v_cmp_le_u32_e32 vcc, v225, v176
	s_nop 1
	v_cndmask_b32_e32 v167, v210, v167, vcc
	v_add_u32_e32 v225, 56, v227
	v_cmp_le_u32_e32 vcc, v225, v176
	s_nop 1
	v_cndmask_b32_e32 v168, v210, v168, vcc
	v_add_u32_e32 v225, 57, v227
	v_cmp_le_u32_e32 vcc, v225, v176
	s_nop 1
	v_cndmask_b32_e32 v169, v210, v169, vcc
	v_add_u32_e32 v225, 58, v227
	v_cmp_le_u32_e32 vcc, v225, v176
	s_nop 1
	v_cndmask_b32_e32 v170, v210, v170, vcc
	v_add_u32_e32 v225, 59, v227
	v_cmp_le_u32_e32 vcc, v225, v176
	s_nop 1
	v_cndmask_b32_e32 v171, v210, v171, vcc
	ds_read_b64_tr_b16 v[236:237], v155
	ds_read_b64_tr_b16 v[238:239], v155 offset:1152
	ds_read_b64_tr_b16 v[244:245], v155 offset:64
	ds_read_b64_tr_b16 v[246:247], v155 offset:1216
	ds_read_b64_tr_b16 v[248:249], v155 offset:2304
	ds_read_b64_tr_b16 v[250:251], v155 offset:3456
	v_exp_f32_e32 v0, v0
	v_exp_f32_e32 v1, v1
	v_exp_f32_e32 v2, v2
	v_exp_f32_e32 v3, v3
	v_add_f32_e32 v224, 0, v0
	v_exp_f32_e32 v4, v4
	v_add_f32_e32 v224, v1, v224
	v_cvt_pk_bf16_f32 v188, v0, v1
	v_exp_f32_e32 v5, v5
	v_add_f32_e32 v224, v2, v224
	v_exp_f32_e32 v6, v6
	v_add_f32_e32 v224, v3, v224
	v_cvt_pk_bf16_f32 v189, v2, v3
	v_exp_f32_e32 v7, v7
	v_add_f32_e32 v224, v4, v224
	v_exp_f32_e32 v8, v8
	v_add_f32_e32 v224, v5, v224
	v_cvt_pk_bf16_f32 v190, v4, v5
	v_exp_f32_e32 v9, v9
	v_add_f32_e32 v224, v6, v224
	v_exp_f32_e32 v10, v10
	v_add_f32_e32 v224, v7, v224
	v_cvt_pk_bf16_f32 v191, v6, v7
	v_exp_f32_e32 v11, v11
	v_add_f32_e32 v224, v8, v224
	v_exp_f32_e32 v12, v12
	v_add_f32_e32 v224, v9, v224
	v_cvt_pk_bf16_f32 v192, v8, v9
	v_exp_f32_e32 v13, v13
	v_add_f32_e32 v224, v10, v224
	v_exp_f32_e32 v14, v14
	v_add_f32_e32 v224, v11, v224
	v_cvt_pk_bf16_f32 v193, v10, v11
	v_exp_f32_e32 v15, v15
	v_add_f32_e32 v224, v12, v224
	v_add_f32_e32 v224, v13, v224
	v_add_f32_e32 v224, v14, v224
	v_add_f32_e32 v224, v15, v224
	v_cvt_pk_bf16_f32 v194, v12, v13
	v_cvt_pk_bf16_f32 v195, v14, v15
	s_nop 1
	s_waitcnt lgkmcnt(4)
; #define MFMA32(a, b, c) __builtin_amdgcn_mfma_f32_32x32x16_bf16((a), (b), (c), 0, 0, 0)
; DI unsigned pk_bf16(float lo, float hi) { f32x2 v = {lo, hi}; bf2_t b = __builtin_convertvector(v, bf2_t); return __builtin_bit_cast(unsigned, b); }
; template <int DQK, bool SB, bool SMAX>
; DI void attn_item(const Params& p, char* smem, int bh, int qb, float Mb) {
;     ...
; #pragma unroll
;       for (int kb = 0; kb < 2; ++kb)
; #pragma unroll
;         for (int s = 0; s < 2; ++s) {
;           u32x4 w;
; #pragma unroll
;           for (int e = 0; e < 4; ++e) w[e] = pk_bf16(st[kb][8 * s + 2 * e], st[kb][8 * s + 2 * e + 1]);
;           pk[kb * 2 + s] = __builtin_bit_cast(bf16x8, w);
;         }
; #pragma unroll
;       for (int kk = 0; kk < 4; ++kk)
; #pragma unroll
;         for (int db = 0; db < 2; ++db) {
;           const s16x4 v0 = __builtin_amdgcn_ds_read_tr16_b64_v4i16((lds_s16x4*)(vc + voff + (16 * kk) * VSTR + 32 * db));
;           const s16x4 v1 = __builtin_amdgcn_ds_read_tr16_b64_v4i16((lds_s16x4*)(vc + voff + (16 * kk + 8) * VSTR + 32 * db));
;           const bf16x8 vf = __builtin_shufflevector(v0, v1, 0, 1, 2, 3, 4, 5, 6, 7);
;           O[db] = MFMA32(vf, pk[kk], O[db]);
;         }
	v_mfma_f32_32x32x16_bf16 v[32:47], v[236:239], v[188:191], v[32:47]
	ds_read_b64_tr_b16 v[236:237], v155 offset:2368
	ds_read_b64_tr_b16 v[238:239], v155 offset:3520
	s_waitcnt lgkmcnt(4)
	v_mfma_f32_32x32x16_bf16 v[16:31], v[244:247], v[188:191], v[16:31]
	ds_read_b64_tr_b16 v[244:245], v155 offset:4608
	ds_read_b64_tr_b16 v[246:247], v155 offset:5760
	s_waitcnt lgkmcnt(4)
	v_mfma_f32_32x32x16_bf16 v[32:47], v[248:251], v[192:195], v[32:47]
	ds_read_b64_tr_b16 v[248:249], v155 offset:4672
	ds_read_b64_tr_b16 v[250:251], v155 offset:5824
	s_waitcnt lgkmcnt(4)
	v_mfma_f32_32x32x16_bf16 v[16:31], v[236:239], v[192:195], v[16:31]
	ds_read_b64_tr_b16 v[236:237], v155 offset:6912
	ds_read_b64_tr_b16 v[238:239], v155 offset:8064
	v_exp_f32_e32 v156, v156
	v_exp_f32_e32 v157, v157
	v_exp_f32_e32 v158, v158
	v_exp_f32_e32 v159, v159
	v_add_f32_e32 v224, v156, v224
	v_exp_f32_e32 v160, v160
	v_add_f32_e32 v224, v157, v224
	v_cvt_pk_bf16_f32 v188, v156, v157
	v_exp_f32_e32 v161, v161
	v_add_f32_e32 v224, v158, v224
	v_exp_f32_e32 v162, v162
	v_add_f32_e32 v224, v159, v224
	v_cvt_pk_bf16_f32 v189, v158, v159
	v_exp_f32_e32 v163, v163
	v_add_f32_e32 v224, v160, v224
	v_exp_f32_e32 v164, v164
	v_add_f32_e32 v224, v161, v224
	v_cvt_pk_bf16_f32 v190, v160, v161
	v_exp_f32_e32 v165, v165
	v_add_f32_e32 v224, v162, v224
	v_exp_f32_e32 v166, v166
	v_add_f32_e32 v224, v163, v224
	v_cvt_pk_bf16_f32 v191, v162, v163
	v_exp_f32_e32 v167, v167
	v_add_f32_e32 v224, v164, v224
	v_exp_f32_e32 v168, v168
	v_add_f32_e32 v224, v165, v224
	v_cvt_pk_bf16_f32 v192, v164, v165
	v_exp_f32_e32 v169, v169
	v_add_f32_e32 v224, v166, v224
	v_exp_f32_e32 v170, v170
	v_add_f32_e32 v224, v167, v224
	v_cvt_pk_bf16_f32 v193, v166, v167
	v_exp_f32_e32 v171, v171
	v_add_f32_e32 v224, v168, v224
	v_add_f32_e32 v224, v169, v224
	v_add_f32_e32 v224, v170, v224
	v_add_f32_e32 v224, v171, v224
	v_cvt_pk_bf16_f32 v194, v168, v169
	v_cvt_pk_bf16_f32 v195, v170, v171
	s_nop 1
	s_waitcnt lgkmcnt(4)
	v_mfma_f32_32x32x16_bf16 v[32:47], v[244:247], v[188:191], v[32:47]
	ds_read_b64_tr_b16 v[244:245], v155 offset:6976
	ds_read_b64_tr_b16 v[246:247], v155 offset:8128
	s_waitcnt lgkmcnt(4)
	v_mfma_f32_32x32x16_bf16 v[16:31], v[248:251], v[188:191], v[16:31]
	s_waitcnt lgkmcnt(2)
	v_mfma_f32_32x32x16_bf16 v[32:47], v[236:239], v[192:195], v[32:47]
	s_waitcnt lgkmcnt(0)
	v_mfma_f32_32x32x16_bf16 v[16:31], v[244:247], v[192:195], v[16:31]
	v_add_f32_e32 v152, v152, v224
	s_waitcnt lgkmcnt(0)
.Lt15_done:
	s_branch .LBB0_424
.LBB0_486:
	v_readlane_b32 s68, v255, 11
	v_readlane_b32 s70, v255, 0
	v_readlane_b32 s69, v255, 12
	v_readlane_b32 s71, v255, 1
	v_readlane_b32 s74, v255, 8
	v_readlane_b32 s75, v255, 7
	v_readlane_b32 s76, v255, 13
